# prologue x->bf16 conversion remapped to 16-byte stores (8 consecutive floats per lane)
# speedup vs baseline: 1.0018x; 1.0018x over previous
.LBB0_85:
	s_cmp_gt_i32 s14, 0x101ff
	s_cbranch_scc1 .LBB0_100
	v_lshlrev_b32_e32 v68, 3, v66
	v_ashrrev_i32_e32 v69, 31, v68
	s_waitcnt vmcnt(5) lgkmcnt(0)
	v_lshl_add_u64 v[2:3], v[68:69], 1, s[12:13]
	s_mov_b64 s[4:5], 0x5d10000
	v_lshl_add_u64 v[70:71], v[2:3], 0, s[4:5]
	s_lshl_b32 s20, s15, 4
	s_mul_i32 s21, s15, 24
	s_branch .LBB0_88

.LBB0_88:
	s_add_i32 s4, s14, 0xffff0000
	s_ashr_i32 s15, s14, 31
	s_cmp_lt_i32 s14, 0x10000
	s_cselect_b32 s6, 0, 8
	s_cselect_b32 s5, s15, 0
	s_cselect_b32 s4, s14, s4
	s_add_u32 s6, s0, s6
	s_addc_u32 s7, s1, 0
	s_load_dwordx2 s[6:7], s[6:7], 0x0
	s_lshl_b64 s[4:5], s[4:5], 12
	s_waitcnt lgkmcnt(0)
	s_add_u32 s4, s6, s4
	s_addc_u32 s5, s7, s5
	v_lshl_add_u64 v[72:73], v[68:69], 2, s[4:5]
	global_load_dwordx4 v[62:65], v[72:73], off
	global_load_dwordx4 v[58:61], v[72:73], off offset:16
	global_load_dwordx4 v[54:57], v[72:73], off offset:2048
	global_load_dwordx4 v[50:53], v[72:73], off offset:2064
	s_add_i32 s4, s14, s27
	s_cmp_lt_i32 s4, 0x10200
	s_cselect_b64 s[6:7], -1, 0
	s_cmp_gt_i32 s4, 0x101ff
	s_cbranch_scc1 .LBB0_90
	s_ashr_i32 s5, s4, 31
	s_add_i32 s8, s4, 0xffff0000
	s_cmp_lt_i32 s4, 0x10000
	s_cselect_b32 s9, s5, 0
	s_cselect_b32 s5, 0, 8
	s_cselect_b32 s8, s4, s8
	s_add_u32 s10, s0, s5
	s_addc_u32 s11, s1, 0
	s_load_dwordx2 s[10:11], s[10:11], 0x0
	s_lshl_b64 s[8:9], s[8:9], 12
	s_waitcnt lgkmcnt(0)
	s_add_u32 s8, s10, s8
	s_addc_u32 s9, s11, s9
	v_lshl_add_u64 v[72:73], v[68:69], 2, s[8:9]
	global_load_dwordx4 v[46:49], v[72:73], off
	global_load_dwordx4 v[42:45], v[72:73], off offset:16
	global_load_dwordx4 v[38:41], v[72:73], off offset:2048
	global_load_dwordx4 v[34:37], v[72:73], off offset:2064
.LBB0_90:
	s_add_i32 s8, s20, s14
	s_cmp_lt_i32 s8, 0x10200
	s_cselect_b64 s[10:11], -1, 0
	s_cmp_gt_i32 s8, 0x101ff
	s_cbranch_scc1 .LBB0_92
	s_ashr_i32 s5, s8, 31
	s_add_i32 s9, s8, 0xffff0000
	s_cmp_lt_i32 s8, 0x10000
	s_cselect_b32 s17, s5, 0
	s_cselect_b32 s5, 0, 8
	s_cselect_b32 s16, s8, s9
	s_add_u32 s18, s0, s5
	s_addc_u32 s19, s1, 0
	s_load_dwordx2 s[18:19], s[18:19], 0x0
	s_lshl_b64 s[16:17], s[16:17], 12
	s_waitcnt lgkmcnt(0)
	s_add_u32 s16, s18, s16
	s_addc_u32 s17, s19, s17
	v_lshl_add_u64 v[72:73], v[68:69], 2, s[16:17]
	global_load_dwordx4 v[30:33], v[72:73], off
	global_load_dwordx4 v[26:29], v[72:73], off offset:16
	global_load_dwordx4 v[22:25], v[72:73], off offset:2048
	global_load_dwordx4 v[18:21], v[72:73], off offset:2064
.LBB0_92:
	s_add_i32 s16, s21, s14
	s_cmp_lt_i32 s16, 0x10200
	s_cselect_b64 s[18:19], -1, 0
	s_cmp_gt_i32 s16, 0x101ff
	s_cbranch_scc1 .LBB0_94
	s_ashr_i32 s5, s16, 31
	s_add_i32 s9, s16, 0xffff0000
	s_cmp_lt_i32 s16, 0x10000
	s_cselect_b32 s23, s5, 0
	s_cselect_b32 s5, 0, 8
	s_cselect_b32 s22, s16, s9
	s_add_u32 s24, s0, s5
	s_addc_u32 s25, s1, 0
	s_load_dwordx2 s[24:25], s[24:25], 0x0
	s_lshl_b64 s[22:23], s[22:23], 12
	s_waitcnt lgkmcnt(0)
	s_add_u32 s22, s24, s22
	s_addc_u32 s23, s25, s23
	v_lshl_add_u64 v[72:73], v[68:69], 2, s[22:23]
	global_load_dwordx4 v[14:17], v[72:73], off
	global_load_dwordx4 v[10:13], v[72:73], off offset:16
	global_load_dwordx4 v[6:9], v[72:73], off offset:2048
	global_load_dwordx4 v[2:5], v[72:73], off offset:2064
.LBB0_94:
	s_lshl_b64 s[14:15], s[14:15], 11
	s_waitcnt vmcnt(0)
	v_cvt_pk_bf16_f32 v62, v62, v63
	v_cvt_pk_bf16_f32 v63, v64, v65
	v_cvt_pk_bf16_f32 v64, v58, v59
	v_cvt_pk_bf16_f32 v65, v60, v61
	v_lshl_add_u64 v[60:61], v[70:71], 0, s[14:15]
	v_cvt_pk_bf16_f32 v54, v54, v55
	v_cvt_pk_bf16_f32 v55, v56, v57
	v_cvt_pk_bf16_f32 v56, v50, v51
	v_cvt_pk_bf16_f32 v57, v52, v53
	s_andn2_b64 vcc, exec, s[6:7]
	global_store_dwordx4 v[60:61], v[62:65], off
	global_store_dwordx4 v[60:61], v[54:57], off offset:1024
	s_cbranch_vccnz .LBB0_97
	s_ashr_i32 s5, s4, 31
	s_lshl_b64 s[6:7], s[4:5], 11
	v_cvt_pk_bf16_f32 v50, v46, v47
	v_cvt_pk_bf16_f32 v51, v48, v49
	v_cvt_pk_bf16_f32 v52, v42, v43
	v_cvt_pk_bf16_f32 v53, v44, v45
	v_lshl_add_u64 v[58:59], v[70:71], 0, s[6:7]
	global_store_dwordx4 v[58:59], v[50:53], off
	v_cvt_pk_bf16_f32 v46, v38, v39
	v_cvt_pk_bf16_f32 v47, v40, v41
	v_cvt_pk_bf16_f32 v48, v34, v35
	v_cvt_pk_bf16_f32 v49, v36, v37
	global_store_dwordx4 v[58:59], v[46:49], off offset:1024
	s_andn2_b64 vcc, exec, s[10:11]
	s_cbranch_vccz .LBB0_98

.LBB0_98:
	s_ashr_i32 s9, s8, 31
	s_lshl_b64 s[6:7], s[8:9], 11
	v_cvt_pk_bf16_f32 v50, v30, v31
	v_cvt_pk_bf16_f32 v51, v32, v33
	v_cvt_pk_bf16_f32 v52, v26, v27
	v_cvt_pk_bf16_f32 v53, v28, v29
	v_lshl_add_u64 v[58:59], v[70:71], 0, s[6:7]
	global_store_dwordx4 v[58:59], v[50:53], off
	v_cvt_pk_bf16_f32 v30, v22, v23
	v_cvt_pk_bf16_f32 v31, v24, v25
	v_cvt_pk_bf16_f32 v32, v18, v19
	v_cvt_pk_bf16_f32 v33, v20, v21
	global_store_dwordx4 v[58:59], v[30:33], off offset:1024
	s_andn2_b64 vcc, exec, s[18:19]
	s_cbranch_vccnz .LBB0_87
.LBB0_99:
	s_ashr_i32 s17, s16, 31
	s_lshl_b64 s[6:7], s[16:17], 11
	v_cvt_pk_bf16_f32 v50, v14, v15
	v_cvt_pk_bf16_f32 v51, v16, v17
	v_cvt_pk_bf16_f32 v52, v10, v11
	v_cvt_pk_bf16_f32 v53, v12, v13
	v_lshl_add_u64 v[58:59], v[70:71], 0, s[6:7]
	global_store_dwordx4 v[58:59], v[50:53], off
	v_cvt_pk_bf16_f32 v14, v6, v7
	v_cvt_pk_bf16_f32 v15, v8, v9
	v_cvt_pk_bf16_f32 v16, v2, v3
	v_cvt_pk_bf16_f32 v17, v4, v5
	global_store_dwordx4 v[58:59], v[14:17], off offset:1024
	s_branch .LBB0_87
